# GEMM K-loop: mid-block s_setprio 0/1 flip pairs deleted (phase-boundary flips kept)
# baseline (speedup 1.0000x reference)
.LBB0_64:
	s_add_i32 s33, s42, 2
	s_add_u32 s46, s40, 0x80
	s_addc_u32 s43, s41, 0
	s_add_i32 s80, 0, 0x10000
	s_cmp_eq_u32 s84, s42
	s_cselect_b32 s43, s1, s43
	s_cselect_b32 s42, s0, s46
	s_cselect_b32 s47, s75, vcc_hi
	s_cselect_b32 s46, s74, vcc_lo
	s_add_i32 s5, 0, 0x14000
	v_add_u32_e32 v140, s80, v185
	v_add_u32_e32 v166, s5, v185
	ds_read_b128 v[128:131], v140
	ds_read_b128 v[132:135], v140 offset:1024
	ds_read_b128 v[136:139], v140 offset:2048
	ds_read_b128 v[140:143], v140 offset:3072
	ds_read_b128 v[144:147], v166
	ds_read_b128 v[148:151], v166 offset:1024
	ds_read_b128 v[152:155], v166 offset:2048
	ds_read_b128 v[166:169], v166 offset:3072
	v_lshl_add_u64 v[182:183], s[40:41], 0, v[162:163]
	s_add_i32 m0, s28, 0xc000
	ds_read_b128 v[170:173], v188
	ds_read_b128 v[174:177], v188 offset:1024
	ds_read_b128 v[178:181], v188 offset:2048
	ds_read_b128 v[214:217], v188 offset:3072
	ds_read_b128 v[218:221], v188 offset:4096
	ds_read_b128 v[222:225], v188 offset:5120
	ds_read_b128 v[226:229], v188 offset:6144
	ds_read_b128 v[230:233], v188 offset:7168
	global_load_lds_dwordx4 v[182:183], off
	v_lshl_add_u64 v[182:183], s[40:41], 0, v[164:165]
	s_add_i32 m0, s28, 0xe000
	s_nop 0
	global_load_lds_dwordx4 v[182:183], off
	s_waitcnt vmcnt(8)
	s_waitcnt lgkmcnt(0)
	s_barrier
	s_setprio 1
	s_waitcnt lgkmcnt(0)
	v_mfma_f32_16x16x32_bf16 v[124:127], v[128:131], v[170:173], v[124:127]
	v_mfma_f32_16x16x32_bf16 v[120:123], v[136:139], v[170:173], v[120:123]
	v_mfma_f32_16x16x32_bf16 v[108:111], v[128:131], v[178:181], v[108:111]
	v_mfma_f32_16x16x32_bf16 v[104:107], v[136:139], v[178:181], v[104:107]
	v_mfma_f32_16x16x32_bf16 v[92:95], v[128:131], v[218:221], v[92:95]
	v_mfma_f32_16x16x32_bf16 v[88:91], v[136:139], v[218:221], v[88:91]
	v_mfma_f32_16x16x32_bf16 v[76:79], v[128:131], v[226:229], v[76:79]
	v_mfma_f32_16x16x32_bf16 v[72:75], v[136:139], v[226:229], v[72:75]
	v_mfma_f32_16x16x32_bf16 v[124:127], v[132:135], v[174:177], v[124:127]
	v_mfma_f32_16x16x32_bf16 v[120:123], v[140:143], v[174:177], v[120:123]
	v_mfma_f32_16x16x32_bf16 v[108:111], v[132:135], v[214:217], v[108:111]
	v_mfma_f32_16x16x32_bf16 v[104:107], v[140:143], v[214:217], v[104:107]
	v_mfma_f32_16x16x32_bf16 v[92:95], v[132:135], v[222:225], v[92:95]
	v_mfma_f32_16x16x32_bf16 v[88:91], v[140:143], v[222:225], v[88:91]
	v_mfma_f32_16x16x32_bf16 v[76:79], v[132:135], v[230:233], v[76:79]
	v_mfma_f32_16x16x32_bf16 v[72:75], v[140:143], v[230:233], v[72:75]
	v_mfma_f32_16x16x32_bf16 v[116:119], v[144:147], v[170:173], v[116:119]
	v_mfma_f32_16x16x32_bf16 v[112:115], v[152:155], v[170:173], v[112:115]
	v_mfma_f32_16x16x32_bf16 v[100:103], v[144:147], v[178:181], v[100:103]
	v_mfma_f32_16x16x32_bf16 v[96:99], v[152:155], v[178:181], v[96:99]
	v_mfma_f32_16x16x32_bf16 v[84:87], v[144:147], v[218:221], v[84:87]
	v_mfma_f32_16x16x32_bf16 v[80:83], v[152:155], v[218:221], v[80:83]
	v_mfma_f32_16x16x32_bf16 v[68:71], v[144:147], v[226:229], v[68:71]
	v_mfma_f32_16x16x32_bf16 v[64:67], v[152:155], v[226:229], v[64:67]
	v_mfma_f32_16x16x32_bf16 v[116:119], v[148:151], v[174:177], v[116:119]
	v_mfma_f32_16x16x32_bf16 v[112:115], v[166:169], v[174:177], v[112:115]
	v_mfma_f32_16x16x32_bf16 v[100:103], v[148:151], v[214:217], v[100:103]
	v_mfma_f32_16x16x32_bf16 v[96:99], v[166:169], v[214:217], v[96:99]
	v_mfma_f32_16x16x32_bf16 v[84:87], v[148:151], v[222:225], v[84:87]
	v_mfma_f32_16x16x32_bf16 v[80:83], v[166:169], v[222:225], v[80:83]
	v_mfma_f32_16x16x32_bf16 v[68:71], v[148:151], v[230:233], v[68:71]
	v_mfma_f32_16x16x32_bf16 v[64:67], v[166:169], v[230:233], v[64:67]
	s_setprio 0
	s_barrier
	s_add_i32 s80, s80, s27
	v_lshl_add_u64 v[182:183], s[46:47], 0, v[192:193]
	s_mov_b32 m0, s80
	ds_read_b128 v[170:173], v188 offset:16384
	ds_read_b128 v[174:177], v188 offset:17408
	ds_read_b128 v[178:181], v188 offset:18432
	ds_read_b128 v[214:217], v188 offset:19456
	ds_read_b128 v[218:221], v188 offset:20480
	ds_read_b128 v[222:225], v188 offset:21504
	ds_read_b128 v[226:229], v188 offset:22528
	ds_read_b128 v[230:233], v188 offset:23552
	global_load_lds_dwordx4 v[182:183], off
	s_add_i32 m0, s80, 0x2000
	v_lshl_add_u64 v[190:191], s[46:47], 0, v[160:161]
	s_add_u32 s46, s46, s30
	s_addc_u32 s47, s47, 0
	s_add_i32 s5, s5, s27
	global_load_lds_dwordx4 v[190:191], off
	v_lshl_add_u64 v[200:201], s[46:47], 0, v[192:193]
	s_mov_b32 m0, s5
	v_lshl_add_u64 v[234:235], s[46:47], 0, v[160:161]
	global_load_lds_dwordx4 v[200:201], off
	s_add_i32 m0, s5, 0x2000
	v_lshl_add_u64 v[236:237], s[42:43], 0, v[156:157]
	global_load_lds_dwordx4 v[234:235], off
	s_mov_b32 m0, s28
	v_lshl_add_u64 v[238:239], s[42:43], 0, v[158:159]
	global_load_lds_dwordx4 v[236:237], off
	s_mov_b32 m0, s69
	s_nop 0
	global_load_lds_dwordx4 v[238:239], off
	s_waitcnt vmcnt(8)
	s_waitcnt lgkmcnt(0)
	s_barrier
	s_setprio 1
	s_waitcnt lgkmcnt(0)
	v_mfma_f32_16x16x32_bf16 v[60:63], v[128:131], v[170:173], v[60:63]
	v_mfma_f32_16x16x32_bf16 v[56:59], v[136:139], v[170:173], v[56:59]
	v_mfma_f32_16x16x32_bf16 v[44:47], v[128:131], v[178:181], v[44:47]
	v_mfma_f32_16x16x32_bf16 v[40:43], v[136:139], v[178:181], v[40:43]
	v_mfma_f32_16x16x32_bf16 v[28:31], v[128:131], v[218:221], v[28:31]
	v_mfma_f32_16x16x32_bf16 v[24:27], v[136:139], v[218:221], v[24:27]
	v_mfma_f32_16x16x32_bf16 v[12:15], v[128:131], v[226:229], v[12:15]
	v_mfma_f32_16x16x32_bf16 v[8:11], v[136:139], v[226:229], v[8:11]
	v_mfma_f32_16x16x32_bf16 v[60:63], v[132:135], v[174:177], v[60:63]
	v_mfma_f32_16x16x32_bf16 v[56:59], v[140:143], v[174:177], v[56:59]
	v_mfma_f32_16x16x32_bf16 v[44:47], v[132:135], v[214:217], v[44:47]
	v_mfma_f32_16x16x32_bf16 v[40:43], v[140:143], v[214:217], v[40:43]
	v_mfma_f32_16x16x32_bf16 v[28:31], v[132:135], v[222:225], v[28:31]
	v_mfma_f32_16x16x32_bf16 v[24:27], v[140:143], v[222:225], v[24:27]
	v_mfma_f32_16x16x32_bf16 v[12:15], v[132:135], v[230:233], v[12:15]
	v_mfma_f32_16x16x32_bf16 v[8:11], v[140:143], v[230:233], v[8:11]
	v_mfma_f32_16x16x32_bf16 v[52:55], v[144:147], v[170:173], v[52:55]
	v_mfma_f32_16x16x32_bf16 v[48:51], v[152:155], v[170:173], v[48:51]
	v_mfma_f32_16x16x32_bf16 v[36:39], v[144:147], v[178:181], v[36:39]
	v_mfma_f32_16x16x32_bf16 v[32:35], v[152:155], v[178:181], v[32:35]
	v_mfma_f32_16x16x32_bf16 v[20:23], v[144:147], v[218:221], v[20:23]
	v_mfma_f32_16x16x32_bf16 v[16:19], v[152:155], v[218:221], v[16:19]
	v_mfma_f32_16x16x32_bf16 v[4:7], v[144:147], v[226:229], v[4:7]
	v_mfma_f32_16x16x32_bf16 v[0:3], v[152:155], v[226:229], v[0:3]
	v_mfma_f32_16x16x32_bf16 v[52:55], v[148:151], v[174:177], v[52:55]
	v_mfma_f32_16x16x32_bf16 v[48:51], v[166:169], v[174:177], v[48:51]
	v_mfma_f32_16x16x32_bf16 v[36:39], v[148:151], v[214:217], v[36:39]
	v_mfma_f32_16x16x32_bf16 v[32:35], v[166:169], v[214:217], v[32:35]
	v_mfma_f32_16x16x32_bf16 v[20:23], v[148:151], v[222:225], v[20:23]
	v_mfma_f32_16x16x32_bf16 v[16:19], v[166:169], v[222:225], v[16:19]
	v_mfma_f32_16x16x32_bf16 v[4:7], v[148:151], v[230:233], v[4:7]
	v_mfma_f32_16x16x32_bf16 v[0:3], v[166:169], v[230:233], v[0:3]
	s_setprio 0
	s_barrier
.Lmy_sp3:
	s_add_i32 s5, 0, 0x18000
	s_add_i32 s46, 0, 0x1c000
	v_add_u32_e32 v140, s5, v185
	v_add_u32_e32 v166, s46, v185
	ds_read_b128 v[128:131], v140
	ds_read_b128 v[132:135], v140 offset:1024
	ds_read_b128 v[136:139], v140 offset:2048
	ds_read_b128 v[140:143], v140 offset:3072
	ds_read_b128 v[144:147], v166
	ds_read_b128 v[148:151], v166 offset:1024
	ds_read_b128 v[152:155], v166 offset:2048
	ds_read_b128 v[166:169], v166 offset:3072
	s_add_u32 s42, s42, s30
	s_addc_u32 s43, s43, 0
	s_mov_b32 m0, s72
	v_lshl_add_u64 v[240:241], s[42:43], 0, v[156:157]
	ds_read_b128 v[170:173], v188 offset:32768
	ds_read_b128 v[174:177], v188 offset:33792
	ds_read_b128 v[178:181], v188 offset:34816
	ds_read_b128 v[214:217], v188 offset:35840
	ds_read_b128 v[218:221], v188 offset:36864
	ds_read_b128 v[222:225], v188 offset:37888
	ds_read_b128 v[226:229], v188 offset:38912
	ds_read_b128 v[230:233], v188 offset:39936
	global_load_lds_dwordx4 v[240:241], off
	v_lshl_add_u64 v[240:241], s[42:43], 0, v[158:159]
	s_mov_b32 m0, s76
	s_nop 0
	global_load_lds_dwordx4 v[240:241], off
	s_waitcnt vmcnt(8)
	s_waitcnt lgkmcnt(0)
	s_barrier
	s_setprio 1
	s_waitcnt lgkmcnt(0)
	v_mfma_f32_16x16x32_bf16 v[124:127], v[128:131], v[170:173], v[124:127]
	v_mfma_f32_16x16x32_bf16 v[120:123], v[136:139], v[170:173], v[120:123]
	v_mfma_f32_16x16x32_bf16 v[108:111], v[128:131], v[178:181], v[108:111]
	v_mfma_f32_16x16x32_bf16 v[104:107], v[136:139], v[178:181], v[104:107]
	v_mfma_f32_16x16x32_bf16 v[92:95], v[128:131], v[218:221], v[92:95]
	v_mfma_f32_16x16x32_bf16 v[88:91], v[136:139], v[218:221], v[88:91]
	v_mfma_f32_16x16x32_bf16 v[76:79], v[128:131], v[226:229], v[76:79]
	v_mfma_f32_16x16x32_bf16 v[72:75], v[136:139], v[226:229], v[72:75]
	v_mfma_f32_16x16x32_bf16 v[124:127], v[132:135], v[174:177], v[124:127]
	v_mfma_f32_16x16x32_bf16 v[120:123], v[140:143], v[174:177], v[120:123]
	v_mfma_f32_16x16x32_bf16 v[108:111], v[132:135], v[214:217], v[108:111]
	v_mfma_f32_16x16x32_bf16 v[104:107], v[140:143], v[214:217], v[104:107]
	v_mfma_f32_16x16x32_bf16 v[92:95], v[132:135], v[222:225], v[92:95]
	v_mfma_f32_16x16x32_bf16 v[88:91], v[140:143], v[222:225], v[88:91]
	v_mfma_f32_16x16x32_bf16 v[76:79], v[132:135], v[230:233], v[76:79]
	v_mfma_f32_16x16x32_bf16 v[72:75], v[140:143], v[230:233], v[72:75]
	v_mfma_f32_16x16x32_bf16 v[116:119], v[144:147], v[170:173], v[116:119]
	v_mfma_f32_16x16x32_bf16 v[112:115], v[152:155], v[170:173], v[112:115]
	v_mfma_f32_16x16x32_bf16 v[100:103], v[144:147], v[178:181], v[100:103]
	v_mfma_f32_16x16x32_bf16 v[96:99], v[152:155], v[178:181], v[96:99]
	v_mfma_f32_16x16x32_bf16 v[84:87], v[144:147], v[218:221], v[84:87]
	v_mfma_f32_16x16x32_bf16 v[80:83], v[152:155], v[218:221], v[80:83]
	v_mfma_f32_16x16x32_bf16 v[68:71], v[144:147], v[226:229], v[68:71]
	v_mfma_f32_16x16x32_bf16 v[64:67], v[152:155], v[226:229], v[64:67]
	v_mfma_f32_16x16x32_bf16 v[116:119], v[148:151], v[174:177], v[116:119]
	v_mfma_f32_16x16x32_bf16 v[112:115], v[166:169], v[174:177], v[112:115]
	v_mfma_f32_16x16x32_bf16 v[100:103], v[148:151], v[214:217], v[100:103]
	v_mfma_f32_16x16x32_bf16 v[96:99], v[166:169], v[214:217], v[96:99]
	v_mfma_f32_16x16x32_bf16 v[84:87], v[148:151], v[222:225], v[84:87]
	v_mfma_f32_16x16x32_bf16 v[80:83], v[166:169], v[222:225], v[80:83]
	v_mfma_f32_16x16x32_bf16 v[68:71], v[148:151], v[230:233], v[68:71]
	v_mfma_f32_16x16x32_bf16 v[64:67], v[166:169], v[230:233], v[64:67]
	s_setprio 0
	s_barrier
	s_add_i32 s5, s5, s27
	v_lshl_add_u64 v[182:183], v[182:183], 0, s[70:71]
	s_mov_b32 m0, s5
	ds_read_b128 v[170:173], v188 offset:49152
	ds_read_b128 v[174:177], v188 offset:50176
	ds_read_b128 v[178:181], v188 offset:51200
	ds_read_b128 v[214:217], v188 offset:52224
	ds_read_b128 v[218:221], v188 offset:53248
	ds_read_b128 v[222:225], v188 offset:54272
	ds_read_b128 v[226:229], v188 offset:55296
	ds_read_b128 v[230:233], v188 offset:56320
	global_load_lds_dwordx4 v[182:183], off
	v_lshl_add_u64 v[182:183], v[190:191], 0, s[70:71]
	s_add_i32 m0, s5, 0x2000
	s_add_i32 s5, s46, s27
	global_load_lds_dwordx4 v[182:183], off
	v_lshl_add_u64 v[182:183], v[200:201], 0, s[70:71]
	s_mov_b32 m0, s5
	s_nop 0
	global_load_lds_dwordx4 v[182:183], off
	v_lshl_add_u64 v[182:183], v[234:235], 0, s[70:71]
	s_add_i32 m0, s5, 0x2000
	s_nop 0
	global_load_lds_dwordx4 v[182:183], off
	v_lshl_add_u64 v[182:183], v[236:237], 0, s[70:71]
	s_mov_b32 m0, s81
	s_nop 0
	global_load_lds_dwordx4 v[182:183], off
	v_lshl_add_u64 v[182:183], v[238:239], 0, s[70:71]
	s_mov_b32 m0, s82
	s_nop 0
	global_load_lds_dwordx4 v[182:183], off
	s_waitcnt vmcnt(8)
	s_waitcnt lgkmcnt(0)
	s_barrier
	s_setprio 1
	s_waitcnt lgkmcnt(0)
	v_mfma_f32_16x16x32_bf16 v[60:63], v[128:131], v[170:173], v[60:63]
	v_mfma_f32_16x16x32_bf16 v[56:59], v[136:139], v[170:173], v[56:59]
	v_mfma_f32_16x16x32_bf16 v[44:47], v[128:131], v[178:181], v[44:47]
	v_mfma_f32_16x16x32_bf16 v[40:43], v[136:139], v[178:181], v[40:43]
	v_mfma_f32_16x16x32_bf16 v[28:31], v[128:131], v[218:221], v[28:31]
	v_mfma_f32_16x16x32_bf16 v[24:27], v[136:139], v[218:221], v[24:27]
	v_mfma_f32_16x16x32_bf16 v[12:15], v[128:131], v[226:229], v[12:15]
	v_mfma_f32_16x16x32_bf16 v[8:11], v[136:139], v[226:229], v[8:11]
	v_mfma_f32_16x16x32_bf16 v[60:63], v[132:135], v[174:177], v[60:63]
	v_mfma_f32_16x16x32_bf16 v[56:59], v[140:143], v[174:177], v[56:59]
	v_mfma_f32_16x16x32_bf16 v[44:47], v[132:135], v[214:217], v[44:47]
	v_mfma_f32_16x16x32_bf16 v[40:43], v[140:143], v[214:217], v[40:43]
	v_mfma_f32_16x16x32_bf16 v[28:31], v[132:135], v[222:225], v[28:31]
	v_mfma_f32_16x16x32_bf16 v[24:27], v[140:143], v[222:225], v[24:27]
	v_mfma_f32_16x16x32_bf16 v[12:15], v[132:135], v[230:233], v[12:15]
	v_mfma_f32_16x16x32_bf16 v[8:11], v[140:143], v[230:233], v[8:11]
	v_mfma_f32_16x16x32_bf16 v[52:55], v[144:147], v[170:173], v[52:55]
	v_mfma_f32_16x16x32_bf16 v[48:51], v[152:155], v[170:173], v[48:51]
	v_mfma_f32_16x16x32_bf16 v[36:39], v[144:147], v[178:181], v[36:39]
	v_mfma_f32_16x16x32_bf16 v[32:35], v[152:155], v[178:181], v[32:35]
	v_mfma_f32_16x16x32_bf16 v[20:23], v[144:147], v[218:221], v[20:23]
	v_mfma_f32_16x16x32_bf16 v[16:19], v[152:155], v[218:221], v[16:19]
	v_mfma_f32_16x16x32_bf16 v[4:7], v[144:147], v[226:229], v[4:7]
	v_mfma_f32_16x16x32_bf16 v[0:3], v[152:155], v[226:229], v[0:3]
	v_mfma_f32_16x16x32_bf16 v[52:55], v[148:151], v[174:177], v[52:55]
	v_mfma_f32_16x16x32_bf16 v[48:51], v[166:169], v[174:177], v[48:51]
	v_mfma_f32_16x16x32_bf16 v[36:39], v[148:151], v[214:217], v[36:39]
	v_mfma_f32_16x16x32_bf16 v[32:35], v[166:169], v[214:217], v[32:35]
	v_mfma_f32_16x16x32_bf16 v[20:23], v[148:151], v[222:225], v[20:23]
	v_mfma_f32_16x16x32_bf16 v[16:19], v[166:169], v[222:225], v[16:19]
	v_mfma_f32_16x16x32_bf16 v[4:7], v[148:151], v[230:233], v[4:7]
	v_mfma_f32_16x16x32_bf16 v[0:3], v[166:169], v[230:233], v[0:3]
	s_setprio 0
	s_barrier
	s_add_u32 s40, s40, 0x100
	s_addc_u32 s41, s41, 0
	s_add_u32 vcc_lo, vcc_lo, 0x100
	s_addc_u32 vcc_hi, vcc_hi, 0
	s_cmp_ge_u32 s33, s78
	s_mov_b32 s42, s33
	s_cbranch_scc0 .LBB0_64
	s_and_b64 vcc, exec, s[66:67]
	s_cbranch_vccz .LBB0_67
	s_barrier

.Lmy_peel:
	s_add_i32 s33, s42, 2
	s_add_u32 s46, s40, 0x80
	s_addc_u32 s43, s41, 0
	s_add_i32 s80, 0, 0x10000
	s_cmp_eq_u32 s84, s42
	s_cselect_b32 s43, s1, s43
	s_cselect_b32 s42, s0, s46
	s_cselect_b32 s47, s75, vcc_hi
	s_cselect_b32 s46, s74, vcc_lo
	s_add_i32 s5, 0, 0x14000
	v_add_u32_e32 v140, s80, v185
	v_add_u32_e32 v166, s5, v185
	ds_read_b128 v[128:131], v140
	ds_read_b128 v[132:135], v140 offset:1024
	ds_read_b128 v[136:139], v140 offset:2048
	ds_read_b128 v[140:143], v140 offset:3072
	ds_read_b128 v[144:147], v166
	ds_read_b128 v[148:151], v166 offset:1024
	ds_read_b128 v[152:155], v166 offset:2048
	ds_read_b128 v[166:169], v166 offset:3072
	v_lshl_add_u64 v[182:183], s[40:41], 0, v[162:163]
	s_add_i32 m0, s28, 0xc000
	ds_read_b128 v[170:173], v188
	ds_read_b128 v[174:177], v188 offset:1024
	ds_read_b128 v[178:181], v188 offset:2048
	ds_read_b128 v[214:217], v188 offset:3072
	ds_read_b128 v[218:221], v188 offset:4096
	ds_read_b128 v[222:225], v188 offset:5120
	ds_read_b128 v[226:229], v188 offset:6144
	ds_read_b128 v[230:233], v188 offset:7168
	global_load_lds_dwordx4 v[182:183], off
	v_lshl_add_u64 v[182:183], s[40:41], 0, v[164:165]
	s_add_i32 m0, s28, 0xe000
	s_nop 0
	global_load_lds_dwordx4 v[182:183], off
	s_waitcnt vmcnt(24)
	s_waitcnt lgkmcnt(0)
	s_barrier
	s_setprio 1
	s_waitcnt lgkmcnt(0)
	v_mfma_f32_16x16x32_bf16 v[124:127], v[128:131], v[170:173], 0
	v_mfma_f32_16x16x32_bf16 v[120:123], v[136:139], v[170:173], 0
	v_mfma_f32_16x16x32_bf16 v[108:111], v[128:131], v[178:181], 0
	v_mfma_f32_16x16x32_bf16 v[104:107], v[136:139], v[178:181], 0
	v_mfma_f32_16x16x32_bf16 v[92:95], v[128:131], v[218:221], 0
	v_mfma_f32_16x16x32_bf16 v[88:91], v[136:139], v[218:221], 0
	v_mfma_f32_16x16x32_bf16 v[76:79], v[128:131], v[226:229], 0
	v_mfma_f32_16x16x32_bf16 v[72:75], v[136:139], v[226:229], 0
	v_mfma_f32_16x16x32_bf16 v[124:127], v[132:135], v[174:177], v[124:127]
	v_mfma_f32_16x16x32_bf16 v[120:123], v[140:143], v[174:177], v[120:123]
	v_mfma_f32_16x16x32_bf16 v[108:111], v[132:135], v[214:217], v[108:111]
	v_mfma_f32_16x16x32_bf16 v[104:107], v[140:143], v[214:217], v[104:107]
	v_mfma_f32_16x16x32_bf16 v[92:95], v[132:135], v[222:225], v[92:95]
	v_mfma_f32_16x16x32_bf16 v[88:91], v[140:143], v[222:225], v[88:91]
	v_mfma_f32_16x16x32_bf16 v[76:79], v[132:135], v[230:233], v[76:79]
	v_mfma_f32_16x16x32_bf16 v[72:75], v[140:143], v[230:233], v[72:75]
	v_mfma_f32_16x16x32_bf16 v[116:119], v[144:147], v[170:173], 0
	v_mfma_f32_16x16x32_bf16 v[112:115], v[152:155], v[170:173], 0
	v_mfma_f32_16x16x32_bf16 v[100:103], v[144:147], v[178:181], 0
	v_mfma_f32_16x16x32_bf16 v[96:99], v[152:155], v[178:181], 0
	v_mfma_f32_16x16x32_bf16 v[84:87], v[144:147], v[218:221], 0
	v_mfma_f32_16x16x32_bf16 v[80:83], v[152:155], v[218:221], 0
	v_mfma_f32_16x16x32_bf16 v[68:71], v[144:147], v[226:229], 0
	v_mfma_f32_16x16x32_bf16 v[64:67], v[152:155], v[226:229], 0
	v_mfma_f32_16x16x32_bf16 v[116:119], v[148:151], v[174:177], v[116:119]
	v_mfma_f32_16x16x32_bf16 v[112:115], v[166:169], v[174:177], v[112:115]
	v_mfma_f32_16x16x32_bf16 v[100:103], v[148:151], v[214:217], v[100:103]
	v_mfma_f32_16x16x32_bf16 v[96:99], v[166:169], v[214:217], v[96:99]
	v_mfma_f32_16x16x32_bf16 v[84:87], v[148:151], v[222:225], v[84:87]
	v_mfma_f32_16x16x32_bf16 v[80:83], v[166:169], v[222:225], v[80:83]
	v_mfma_f32_16x16x32_bf16 v[68:71], v[148:151], v[230:233], v[68:71]
	v_mfma_f32_16x16x32_bf16 v[64:67], v[166:169], v[230:233], v[64:67]
	s_setprio 0
	s_barrier
	s_add_i32 s80, s80, s27
	v_lshl_add_u64 v[182:183], s[46:47], 0, v[192:193]
	s_mov_b32 m0, s80
	ds_read_b128 v[170:173], v188 offset:16384
	ds_read_b128 v[174:177], v188 offset:17408
	ds_read_b128 v[178:181], v188 offset:18432
	ds_read_b128 v[214:217], v188 offset:19456
	ds_read_b128 v[218:221], v188 offset:20480
	ds_read_b128 v[222:225], v188 offset:21504
	ds_read_b128 v[226:229], v188 offset:22528
	ds_read_b128 v[230:233], v188 offset:23552
	global_load_lds_dwordx4 v[182:183], off
	s_add_i32 m0, s80, 0x2000
	v_lshl_add_u64 v[190:191], s[46:47], 0, v[160:161]
	s_add_u32 s46, s46, s30
	s_addc_u32 s47, s47, 0
	s_add_i32 s5, s5, s27
	global_load_lds_dwordx4 v[190:191], off
	v_lshl_add_u64 v[200:201], s[46:47], 0, v[192:193]
	s_mov_b32 m0, s5
	v_lshl_add_u64 v[234:235], s[46:47], 0, v[160:161]
	global_load_lds_dwordx4 v[200:201], off
	s_add_i32 m0, s5, 0x2000
	v_lshl_add_u64 v[236:237], s[42:43], 0, v[156:157]
	global_load_lds_dwordx4 v[234:235], off
	s_mov_b32 m0, s28
	v_lshl_add_u64 v[238:239], s[42:43], 0, v[158:159]
	global_load_lds_dwordx4 v[236:237], off
	s_mov_b32 m0, s69
	s_nop 0
	global_load_lds_dwordx4 v[238:239], off
	s_waitcnt vmcnt(24)
	s_waitcnt lgkmcnt(0)
	s_barrier
	s_setprio 1
	s_waitcnt lgkmcnt(0)
	v_mfma_f32_16x16x32_bf16 v[60:63], v[128:131], v[170:173], 0
	v_mfma_f32_16x16x32_bf16 v[56:59], v[136:139], v[170:173], 0
	v_mfma_f32_16x16x32_bf16 v[44:47], v[128:131], v[178:181], 0
	v_mfma_f32_16x16x32_bf16 v[40:43], v[136:139], v[178:181], 0
	v_mfma_f32_16x16x32_bf16 v[28:31], v[128:131], v[218:221], 0
	v_mfma_f32_16x16x32_bf16 v[24:27], v[136:139], v[218:221], 0
	v_mfma_f32_16x16x32_bf16 v[12:15], v[128:131], v[226:229], 0
	v_mfma_f32_16x16x32_bf16 v[8:11], v[136:139], v[226:229], 0
	v_mfma_f32_16x16x32_bf16 v[60:63], v[132:135], v[174:177], v[60:63]
	v_mfma_f32_16x16x32_bf16 v[56:59], v[140:143], v[174:177], v[56:59]
	v_mfma_f32_16x16x32_bf16 v[44:47], v[132:135], v[214:217], v[44:47]
	v_mfma_f32_16x16x32_bf16 v[40:43], v[140:143], v[214:217], v[40:43]
	v_mfma_f32_16x16x32_bf16 v[28:31], v[132:135], v[222:225], v[28:31]
	v_mfma_f32_16x16x32_bf16 v[24:27], v[140:143], v[222:225], v[24:27]
	v_mfma_f32_16x16x32_bf16 v[12:15], v[132:135], v[230:233], v[12:15]
	v_mfma_f32_16x16x32_bf16 v[8:11], v[140:143], v[230:233], v[8:11]
	v_mfma_f32_16x16x32_bf16 v[52:55], v[144:147], v[170:173], 0
	v_mfma_f32_16x16x32_bf16 v[48:51], v[152:155], v[170:173], 0
	v_mfma_f32_16x16x32_bf16 v[36:39], v[144:147], v[178:181], 0
	v_mfma_f32_16x16x32_bf16 v[32:35], v[152:155], v[178:181], 0
	v_mfma_f32_16x16x32_bf16 v[20:23], v[144:147], v[218:221], 0
	v_mfma_f32_16x16x32_bf16 v[16:19], v[152:155], v[218:221], 0
	v_mfma_f32_16x16x32_bf16 v[4:7], v[144:147], v[226:229], 0
	v_mfma_f32_16x16x32_bf16 v[0:3], v[152:155], v[226:229], 0
	v_mfma_f32_16x16x32_bf16 v[52:55], v[148:151], v[174:177], v[52:55]
	v_mfma_f32_16x16x32_bf16 v[48:51], v[166:169], v[174:177], v[48:51]
	v_mfma_f32_16x16x32_bf16 v[36:39], v[148:151], v[214:217], v[36:39]
	v_mfma_f32_16x16x32_bf16 v[32:35], v[166:169], v[214:217], v[32:35]
	v_mfma_f32_16x16x32_bf16 v[20:23], v[148:151], v[222:225], v[20:23]
	v_mfma_f32_16x16x32_bf16 v[16:19], v[166:169], v[222:225], v[16:19]
	v_mfma_f32_16x16x32_bf16 v[4:7], v[148:151], v[230:233], v[4:7]
	v_mfma_f32_16x16x32_bf16 v[0:3], v[166:169], v[230:233], v[0:3]
	s_setprio 0
	s_barrier
	s_branch .Lmy_sp3
